# FFN-up SwiGLU epilogue regenerated with packed f32 mul/add (same ops per element), 8 outputs per store group in flight
# baseline (speedup 1.0000x reference)
; __device__ __forceinline__ unsigned cvt_pk_bf16(float lo, float hi) { unsigned r; asm volatile("v_cvt_pk_bf16_f32 %0, %1, %2" : "=v"(r) : "v"(lo), "v"(hi)); return r; }
;     __device__ __forceinline__ void operator()(const f32x4 (&acc)[2][2][4][2], const Unit& u, int wr, int wc, int fr, int fq) const {
;         const int row0 = u.pm * BM + wr * 64 + fr, col0 = u.pn * HALF + wc * 32 + 8 * fq;
; #pragma unroll
;         for (int ai = 0; ai < 2; ++ai)
; #pragma unroll
;             for (int m = 0; m < 4; ++m) {
;                 bf16_t* rowp = O + (size_t)(row0 + ai * HALF + m * 16) * ldc + col0;
;                 const f32x4 a0 = acc[ai][0][m][0], a1 = acc[ai][0][m][1], b0 = acc[ai][1][m][0], b1 = acc[ai][1][m][1];
;                 float r[8];
; #pragma unroll
;                 for (int j = 0; j < 4; ++j) { r[j] = a0[j] * __builtin_amdgcn_rcpf(1.f + __expf(-a0[j])) * b0[j]; r[4 + j] = a1[j] * __builtin_amdgcn_rcpf(1.f + __expf(-a1[j])) * b1[j]; }
;                 u32x4 w; w.x = cvt_pk_bf16(r[0], r[1]); w.y = cvt_pk_bf16(r[2], r[3]); w.z = cvt_pk_bf16(r[4], r[5]); w.w = cvt_pk_bf16(r[6], r[7]);
;                 *(u32x4*)rowp = w;
;                 asm volatile("" ::: "memory");
;             }
;     }
.LBB0_356:
	s_mov_b32 s98, 0xbfb8aa3b
	v_lshl_or_b32 v150, s19, 7, v146
	v_lshl_add_u32 v148, s18, 8, v132
	v_ashrrev_i32_e32 v151, 31, v150
	v_mov_b64_e32 v[144:145], s[4:5]
	v_mad_i64_i32 v[152:153], s[18:19], v148, s88, v[144:145]
	s_andn2_b64 vcc, exec, s[6:7]
	v_pk_mul_f32 v[198:199], v[128:129], s[98:99] op_sel_hi:[1,0]
	v_pk_mul_f32 v[200:201], v[130:131], s[98:99] op_sel_hi:[1,0]
	v_pk_mul_f32 v[202:203], v[120:121], s[98:99] op_sel_hi:[1,0]
	v_pk_mul_f32 v[204:205], v[122:123], s[98:99] op_sel_hi:[1,0]
	v_exp_f32_e32 v198, v198
	v_exp_f32_e32 v199, v199
	v_exp_f32_e32 v200, v200
	v_exp_f32_e32 v201, v201
	v_exp_f32_e32 v202, v202
	v_exp_f32_e32 v203, v203
	v_exp_f32_e32 v204, v204
	v_exp_f32_e32 v205, v205
	v_pk_add_f32 v[198:199], v[198:199], 1.0 op_sel_hi:[1,0]
	v_pk_add_f32 v[200:201], v[200:201], 1.0 op_sel_hi:[1,0]
	v_pk_add_f32 v[202:203], v[202:203], 1.0 op_sel_hi:[1,0]
	v_pk_add_f32 v[204:205], v[204:205], 1.0 op_sel_hi:[1,0]
	v_rcp_f32_e32 v198, v198
	v_rcp_f32_e32 v199, v199
	v_rcp_f32_e32 v200, v200
	v_rcp_f32_e32 v201, v201
	v_rcp_f32_e32 v202, v202
	v_rcp_f32_e32 v203, v203
	v_rcp_f32_e32 v204, v204
	v_rcp_f32_e32 v205, v205
	v_pk_mul_f32 v[198:199], v[128:129], v[198:199]
	v_pk_mul_f32 v[200:201], v[130:131], v[200:201]
	v_pk_mul_f32 v[202:203], v[120:121], v[202:203]
	v_pk_mul_f32 v[204:205], v[122:123], v[204:205]
	v_pk_mul_f32 v[198:199], v[198:199], v[124:125]
	v_pk_mul_f32 v[200:201], v[200:201], v[126:127]
	v_pk_mul_f32 v[202:203], v[202:203], v[116:117]
	v_pk_mul_f32 v[204:205], v[204:205], v[118:119]
	v_cvt_pk_bf16_f32 v118, v198, v199
	v_cvt_pk_bf16_f32 v119, v200, v201
	v_cvt_pk_bf16_f32 v120, v202, v203
	v_cvt_pk_bf16_f32 v121, v204, v205
	v_lshlrev_b64 v[116:117], 1, v[150:151]
	v_lshl_add_u64 v[122:123], v[152:153], 0, v[116:117]
	global_store_dwordx4 v[122:123], v[118:121], off
	s_nop 1
	v_or_b32_e32 v118, 16, v148
	v_mad_i64_i32 v[118:119], s[18:19], v118, s88, v[144:145]
	v_pk_mul_f32 v[206:207], v[112:113], s[98:99] op_sel_hi:[1,0]
	v_pk_mul_f32 v[208:209], v[114:115], s[98:99] op_sel_hi:[1,0]
	v_pk_mul_f32 v[210:211], v[104:105], s[98:99] op_sel_hi:[1,0]
	v_pk_mul_f32 v[212:213], v[106:107], s[98:99] op_sel_hi:[1,0]
	v_exp_f32_e32 v206, v206
	v_exp_f32_e32 v207, v207
	v_exp_f32_e32 v208, v208
	v_exp_f32_e32 v209, v209
	v_exp_f32_e32 v210, v210
	v_exp_f32_e32 v211, v211
	v_exp_f32_e32 v212, v212
	v_exp_f32_e32 v213, v213
	v_pk_add_f32 v[206:207], v[206:207], 1.0 op_sel_hi:[1,0]
	v_pk_add_f32 v[208:209], v[208:209], 1.0 op_sel_hi:[1,0]
	v_pk_add_f32 v[210:211], v[210:211], 1.0 op_sel_hi:[1,0]
	v_pk_add_f32 v[212:213], v[212:213], 1.0 op_sel_hi:[1,0]
	v_rcp_f32_e32 v206, v206
	v_rcp_f32_e32 v207, v207
	v_rcp_f32_e32 v208, v208
	v_rcp_f32_e32 v209, v209
	v_rcp_f32_e32 v210, v210
	v_rcp_f32_e32 v211, v211
	v_rcp_f32_e32 v212, v212
	v_rcp_f32_e32 v213, v213
	v_pk_mul_f32 v[206:207], v[112:113], v[206:207]
	v_pk_mul_f32 v[208:209], v[114:115], v[208:209]
	v_pk_mul_f32 v[210:211], v[104:105], v[210:211]
	v_pk_mul_f32 v[212:213], v[106:107], v[212:213]
	v_pk_mul_f32 v[206:207], v[206:207], v[108:109]
	v_pk_mul_f32 v[208:209], v[208:209], v[110:111]
	v_pk_mul_f32 v[210:211], v[210:211], v[100:101]
	v_pk_mul_f32 v[212:213], v[212:213], v[102:103]
	v_cvt_pk_bf16_f32 v100, v206, v207
	v_cvt_pk_bf16_f32 v101, v208, v209
	v_cvt_pk_bf16_f32 v102, v210, v211
	v_cvt_pk_bf16_f32 v103, v212, v213
	v_lshl_add_u64 v[104:105], v[118:119], 0, v[116:117]
	global_store_dwordx4 v[104:105], v[100:103], off
	s_nop 1
	v_or_b32_e32 v100, 32, v148
	v_mad_i64_i32 v[100:101], s[18:19], v100, s88, v[144:145]
	v_pk_mul_f32 v[198:199], v[96:97], s[98:99] op_sel_hi:[1,0]
	v_pk_mul_f32 v[200:201], v[98:99], s[98:99] op_sel_hi:[1,0]
	v_pk_mul_f32 v[202:203], v[88:89], s[98:99] op_sel_hi:[1,0]
	v_pk_mul_f32 v[204:205], v[90:91], s[98:99] op_sel_hi:[1,0]
	v_exp_f32_e32 v198, v198
	v_exp_f32_e32 v199, v199
	v_exp_f32_e32 v200, v200
	v_exp_f32_e32 v201, v201
	v_exp_f32_e32 v202, v202
	v_exp_f32_e32 v203, v203
	v_exp_f32_e32 v204, v204
	v_exp_f32_e32 v205, v205
	v_pk_add_f32 v[198:199], v[198:199], 1.0 op_sel_hi:[1,0]
	v_pk_add_f32 v[200:201], v[200:201], 1.0 op_sel_hi:[1,0]
	v_pk_add_f32 v[202:203], v[202:203], 1.0 op_sel_hi:[1,0]
	v_pk_add_f32 v[204:205], v[204:205], 1.0 op_sel_hi:[1,0]
	v_rcp_f32_e32 v198, v198
	v_rcp_f32_e32 v199, v199
	v_rcp_f32_e32 v200, v200
	v_rcp_f32_e32 v201, v201
	v_rcp_f32_e32 v202, v202
	v_rcp_f32_e32 v203, v203
	v_rcp_f32_e32 v204, v204
	v_rcp_f32_e32 v205, v205
	v_pk_mul_f32 v[198:199], v[96:97], v[198:199]
	v_pk_mul_f32 v[200:201], v[98:99], v[200:201]
	v_pk_mul_f32 v[202:203], v[88:89], v[202:203]
	v_pk_mul_f32 v[204:205], v[90:91], v[204:205]
	v_pk_mul_f32 v[198:199], v[198:199], v[92:93]
	v_pk_mul_f32 v[200:201], v[200:201], v[94:95]
	v_pk_mul_f32 v[202:203], v[202:203], v[84:85]
	v_pk_mul_f32 v[204:205], v[204:205], v[86:87]
	v_cvt_pk_bf16_f32 v84, v198, v199
	v_cvt_pk_bf16_f32 v85, v200, v201
	v_cvt_pk_bf16_f32 v86, v202, v203
	v_cvt_pk_bf16_f32 v87, v204, v205
	v_lshl_add_u64 v[88:89], v[100:101], 0, v[116:117]
	global_store_dwordx4 v[88:89], v[84:87], off
	s_nop 1
	v_or_b32_e32 v84, 48, v148
	v_mad_i64_i32 v[84:85], s[18:19], v84, s88, v[144:145]
	v_pk_mul_f32 v[206:207], v[80:81], s[98:99] op_sel_hi:[1,0]
	v_pk_mul_f32 v[208:209], v[82:83], s[98:99] op_sel_hi:[1,0]
	v_pk_mul_f32 v[210:211], v[72:73], s[98:99] op_sel_hi:[1,0]
	v_pk_mul_f32 v[212:213], v[74:75], s[98:99] op_sel_hi:[1,0]
	v_exp_f32_e32 v206, v206
	v_exp_f32_e32 v207, v207
	v_exp_f32_e32 v208, v208
	v_exp_f32_e32 v209, v209
	v_exp_f32_e32 v210, v210
	v_exp_f32_e32 v211, v211
	v_exp_f32_e32 v212, v212
	v_exp_f32_e32 v213, v213
; __device__ __forceinline__ unsigned cvt_pk_bf16(float lo, float hi) { unsigned r; asm volatile("v_cvt_pk_bf16_f32 %0, %1, %2" : "=v"(r) : "v"(lo), "v"(hi)); return r; }
;     __device__ __forceinline__ void operator()(const f32x4 (&acc)[2][2][4][2], const Unit& u, int wr, int wc, int fr, int fq) const {
;     ...
;             for (int m = 0; m < 4; ++m) {
;                 bf16_t* rowp = O + (size_t)(row0 + ai * HALF + m * 16) * ldc + col0;
;                 const f32x4 a0 = acc[ai][0][m][0], a1 = acc[ai][0][m][1], b0 = acc[ai][1][m][0], b1 = acc[ai][1][m][1];
;                 float r[8];
; #pragma unroll
;                 for (int j = 0; j < 4; ++j) { r[j] = a0[j] * __builtin_amdgcn_rcpf(1.f + __expf(-a0[j])) * b0[j]; r[4 + j] = a1[j] * __builtin_amdgcn_rcpf(1.f + __expf(-a1[j])) * b1[j]; }
;                 u32x4 w; w.x = cvt_pk_bf16(r[0], r[1]); w.y = cvt_pk_bf16(r[2], r[3]); w.z = cvt_pk_bf16(r[4], r[5]); w.w = cvt_pk_bf16(r[6], r[7]);
;                 *(u32x4*)rowp = w;
;                 asm volatile("" ::: "memory");
;             }
	v_pk_add_f32 v[206:207], v[206:207], 1.0 op_sel_hi:[1,0]
	v_pk_add_f32 v[208:209], v[208:209], 1.0 op_sel_hi:[1,0]
	v_pk_add_f32 v[210:211], v[210:211], 1.0 op_sel_hi:[1,0]
	v_pk_add_f32 v[212:213], v[212:213], 1.0 op_sel_hi:[1,0]
	v_rcp_f32_e32 v206, v206
	v_rcp_f32_e32 v207, v207
	v_rcp_f32_e32 v208, v208
	v_rcp_f32_e32 v209, v209
	v_rcp_f32_e32 v210, v210
	v_rcp_f32_e32 v211, v211
	v_rcp_f32_e32 v212, v212
	v_rcp_f32_e32 v213, v213
	v_pk_mul_f32 v[206:207], v[80:81], v[206:207]
	v_pk_mul_f32 v[208:209], v[82:83], v[208:209]
	v_pk_mul_f32 v[210:211], v[72:73], v[210:211]
	v_pk_mul_f32 v[212:213], v[74:75], v[212:213]
	v_pk_mul_f32 v[206:207], v[206:207], v[76:77]
	v_pk_mul_f32 v[208:209], v[208:209], v[78:79]
	v_pk_mul_f32 v[210:211], v[210:211], v[68:69]
	v_pk_mul_f32 v[212:213], v[212:213], v[70:71]
	v_cvt_pk_bf16_f32 v68, v206, v207
	v_cvt_pk_bf16_f32 v69, v208, v209
	v_cvt_pk_bf16_f32 v70, v210, v211
	v_cvt_pk_bf16_f32 v71, v212, v213
	v_lshl_add_u64 v[72:73], v[84:85], 0, v[116:117]
	global_store_dwordx4 v[72:73], v[68:71], off
	s_nop 1
	v_add_u32_e32 v68, 0x80, v148
	v_mad_i64_i32 v[68:69], s[18:19], v68, s88, v[144:145]
	v_pk_mul_f32 v[198:199], v[64:65], s[98:99] op_sel_hi:[1,0]
	v_pk_mul_f32 v[200:201], v[66:67], s[98:99] op_sel_hi:[1,0]
	v_pk_mul_f32 v[202:203], v[56:57], s[98:99] op_sel_hi:[1,0]
	v_pk_mul_f32 v[204:205], v[58:59], s[98:99] op_sel_hi:[1,0]
	v_exp_f32_e32 v198, v198
	v_exp_f32_e32 v199, v199
	v_exp_f32_e32 v200, v200
	v_exp_f32_e32 v201, v201
	v_exp_f32_e32 v202, v202
	v_exp_f32_e32 v203, v203
	v_exp_f32_e32 v204, v204
	v_exp_f32_e32 v205, v205
	v_pk_add_f32 v[198:199], v[198:199], 1.0 op_sel_hi:[1,0]
	v_pk_add_f32 v[200:201], v[200:201], 1.0 op_sel_hi:[1,0]
	v_pk_add_f32 v[202:203], v[202:203], 1.0 op_sel_hi:[1,0]
	v_pk_add_f32 v[204:205], v[204:205], 1.0 op_sel_hi:[1,0]
	v_rcp_f32_e32 v198, v198
	v_rcp_f32_e32 v199, v199
	v_rcp_f32_e32 v200, v200
	v_rcp_f32_e32 v201, v201
	v_rcp_f32_e32 v202, v202
	v_rcp_f32_e32 v203, v203
	v_rcp_f32_e32 v204, v204
	v_rcp_f32_e32 v205, v205
	v_pk_mul_f32 v[198:199], v[64:65], v[198:199]
	v_pk_mul_f32 v[200:201], v[66:67], v[200:201]
	v_pk_mul_f32 v[202:203], v[56:57], v[202:203]
	v_pk_mul_f32 v[204:205], v[58:59], v[204:205]
	v_pk_mul_f32 v[198:199], v[198:199], v[60:61]
	v_pk_mul_f32 v[200:201], v[200:201], v[62:63]
	v_pk_mul_f32 v[202:203], v[202:203], v[52:53]
	v_pk_mul_f32 v[204:205], v[204:205], v[54:55]
	v_cvt_pk_bf16_f32 v52, v198, v199
	v_cvt_pk_bf16_f32 v53, v200, v201
	v_cvt_pk_bf16_f32 v54, v202, v203
	v_cvt_pk_bf16_f32 v55, v204, v205
	v_lshl_add_u64 v[56:57], v[68:69], 0, v[116:117]
	global_store_dwordx4 v[56:57], v[52:55], off
	s_nop 1
	v_add_u32_e32 v52, 0x90, v148
	v_mad_i64_i32 v[52:53], s[18:19], v52, s88, v[144:145]
	v_pk_mul_f32 v[206:207], v[48:49], s[98:99] op_sel_hi:[1,0]
	v_pk_mul_f32 v[208:209], v[50:51], s[98:99] op_sel_hi:[1,0]
	v_pk_mul_f32 v[210:211], v[40:41], s[98:99] op_sel_hi:[1,0]
	v_pk_mul_f32 v[212:213], v[42:43], s[98:99] op_sel_hi:[1,0]
	v_exp_f32_e32 v206, v206
	v_exp_f32_e32 v207, v207
	v_exp_f32_e32 v208, v208
	v_exp_f32_e32 v209, v209
	v_exp_f32_e32 v210, v210
	v_exp_f32_e32 v211, v211
	v_exp_f32_e32 v212, v212
	v_exp_f32_e32 v213, v213
	v_pk_add_f32 v[206:207], v[206:207], 1.0 op_sel_hi:[1,0]
	v_pk_add_f32 v[208:209], v[208:209], 1.0 op_sel_hi:[1,0]
	v_pk_add_f32 v[210:211], v[210:211], 1.0 op_sel_hi:[1,0]
	v_pk_add_f32 v[212:213], v[212:213], 1.0 op_sel_hi:[1,0]
	v_rcp_f32_e32 v206, v206
	v_rcp_f32_e32 v207, v207
	v_rcp_f32_e32 v208, v208
	v_rcp_f32_e32 v209, v209
	v_rcp_f32_e32 v210, v210
	v_rcp_f32_e32 v211, v211
	v_rcp_f32_e32 v212, v212
	v_rcp_f32_e32 v213, v213
	v_pk_mul_f32 v[206:207], v[48:49], v[206:207]
	v_pk_mul_f32 v[208:209], v[50:51], v[208:209]
	v_pk_mul_f32 v[210:211], v[40:41], v[210:211]
; __device__ __forceinline__ unsigned cvt_pk_bf16(float lo, float hi) { unsigned r; asm volatile("v_cvt_pk_bf16_f32 %0, %1, %2" : "=v"(r) : "v"(lo), "v"(hi)); return r; }
; template <class Epi, class Sched, bool ALIGN_EPI = false, bool SP2 = false>
; __device__ __forceinline__ void gemm_phase(PG8_LAS unsigned char* lds, const Gemm g, const Sched& S, const Epi& E) {
;     ...
;         if constexpr (!Epi::AFTER_DRAIN) { E(acc, cur, wr, wc, fr, fq); S.done(cur); }
;         if (!has_next) break;
;     __device__ __forceinline__ void operator()(const f32x4 (&acc)[2][2][4][2], const Unit& u, int wr, int wc, int fr, int fq) const {
;     ...
;             for (int m = 0; m < 4; ++m) {
;                 bf16_t* rowp = O + (size_t)(row0 + ai * HALF + m * 16) * ldc + col0;
;                 const f32x4 a0 = acc[ai][0][m][0], a1 = acc[ai][0][m][1], b0 = acc[ai][1][m][0], b1 = acc[ai][1][m][1];
;                 float r[8];
; #pragma unroll
;                 for (int j = 0; j < 4; ++j) { r[j] = a0[j] * __builtin_amdgcn_rcpf(1.f + __expf(-a0[j])) * b0[j]; r[4 + j] = a1[j] * __builtin_amdgcn_rcpf(1.f + __expf(-a1[j])) * b1[j]; }
;                 u32x4 w; w.x = cvt_pk_bf16(r[0], r[1]); w.y = cvt_pk_bf16(r[2], r[3]); w.z = cvt_pk_bf16(r[4], r[5]); w.w = cvt_pk_bf16(r[6], r[7]);
;                 *(u32x4*)rowp = w;
;                 asm volatile("" ::: "memory");
;             }
	v_pk_mul_f32 v[212:213], v[42:43], v[212:213]
	v_pk_mul_f32 v[206:207], v[206:207], v[44:45]
	v_pk_mul_f32 v[208:209], v[208:209], v[46:47]
	v_pk_mul_f32 v[210:211], v[210:211], v[36:37]
	v_pk_mul_f32 v[212:213], v[212:213], v[38:39]
	v_cvt_pk_bf16_f32 v36, v206, v207
	v_cvt_pk_bf16_f32 v37, v208, v209
	v_cvt_pk_bf16_f32 v38, v210, v211
	v_cvt_pk_bf16_f32 v39, v212, v213
	v_lshl_add_u64 v[40:41], v[52:53], 0, v[116:117]
	global_store_dwordx4 v[40:41], v[36:39], off
	s_nop 1
	v_add_u32_e32 v36, 0xa0, v148
	v_mad_i64_i32 v[36:37], s[18:19], v36, s88, v[144:145]
	v_pk_mul_f32 v[198:199], v[32:33], s[98:99] op_sel_hi:[1,0]
	v_pk_mul_f32 v[200:201], v[34:35], s[98:99] op_sel_hi:[1,0]
	v_pk_mul_f32 v[202:203], v[24:25], s[98:99] op_sel_hi:[1,0]
	v_pk_mul_f32 v[204:205], v[26:27], s[98:99] op_sel_hi:[1,0]
	v_exp_f32_e32 v198, v198
	v_exp_f32_e32 v199, v199
	v_exp_f32_e32 v200, v200
	v_exp_f32_e32 v201, v201
	v_exp_f32_e32 v202, v202
	v_exp_f32_e32 v203, v203
	v_exp_f32_e32 v204, v204
	v_exp_f32_e32 v205, v205
	v_pk_add_f32 v[198:199], v[198:199], 1.0 op_sel_hi:[1,0]
	v_pk_add_f32 v[200:201], v[200:201], 1.0 op_sel_hi:[1,0]
	v_pk_add_f32 v[202:203], v[202:203], 1.0 op_sel_hi:[1,0]
	v_pk_add_f32 v[204:205], v[204:205], 1.0 op_sel_hi:[1,0]
	v_rcp_f32_e32 v198, v198
	v_rcp_f32_e32 v199, v199
	v_rcp_f32_e32 v200, v200
	v_rcp_f32_e32 v201, v201
	v_rcp_f32_e32 v202, v202
	v_rcp_f32_e32 v203, v203
	v_rcp_f32_e32 v204, v204
	v_rcp_f32_e32 v205, v205
	v_pk_mul_f32 v[198:199], v[32:33], v[198:199]
	v_pk_mul_f32 v[200:201], v[34:35], v[200:201]
	v_pk_mul_f32 v[202:203], v[24:25], v[202:203]
	v_pk_mul_f32 v[204:205], v[26:27], v[204:205]
	v_pk_mul_f32 v[198:199], v[198:199], v[28:29]
	v_pk_mul_f32 v[200:201], v[200:201], v[30:31]
	v_pk_mul_f32 v[202:203], v[202:203], v[20:21]
	v_pk_mul_f32 v[204:205], v[204:205], v[22:23]
	v_cvt_pk_bf16_f32 v20, v198, v199
	v_cvt_pk_bf16_f32 v21, v200, v201
	v_cvt_pk_bf16_f32 v22, v202, v203
	v_cvt_pk_bf16_f32 v23, v204, v205
	v_lshl_add_u64 v[24:25], v[36:37], 0, v[116:117]
	global_store_dwordx4 v[24:25], v[20:23], off
	s_nop 1
	v_add_u32_e32 v20, 0xb0, v148
	v_mad_i64_i32 v[20:21], s[18:19], v20, s88, v[144:145]
	s_mov_b64 s[18:19], -1
	v_pk_mul_f32 v[206:207], v[16:17], s[98:99] op_sel_hi:[1,0]
	v_pk_mul_f32 v[208:209], v[18:19], s[98:99] op_sel_hi:[1,0]
	v_pk_mul_f32 v[210:211], v[8:9], s[98:99] op_sel_hi:[1,0]
	v_pk_mul_f32 v[212:213], v[10:11], s[98:99] op_sel_hi:[1,0]
	v_exp_f32_e32 v206, v206
	v_exp_f32_e32 v207, v207
	v_exp_f32_e32 v208, v208
	v_exp_f32_e32 v209, v209
	v_exp_f32_e32 v210, v210
	v_exp_f32_e32 v211, v211
	v_exp_f32_e32 v212, v212
	v_exp_f32_e32 v213, v213
	v_pk_add_f32 v[206:207], v[206:207], 1.0 op_sel_hi:[1,0]
	v_pk_add_f32 v[208:209], v[208:209], 1.0 op_sel_hi:[1,0]
	v_pk_add_f32 v[210:211], v[210:211], 1.0 op_sel_hi:[1,0]
	v_pk_add_f32 v[212:213], v[212:213], 1.0 op_sel_hi:[1,0]
	v_rcp_f32_e32 v206, v206
	v_rcp_f32_e32 v207, v207
	v_rcp_f32_e32 v208, v208
	v_rcp_f32_e32 v209, v209
	v_rcp_f32_e32 v210, v210
	v_rcp_f32_e32 v211, v211
	v_rcp_f32_e32 v212, v212
	v_rcp_f32_e32 v213, v213
	v_pk_mul_f32 v[206:207], v[16:17], v[206:207]
	v_pk_mul_f32 v[208:209], v[18:19], v[208:209]
	v_pk_mul_f32 v[210:211], v[8:9], v[210:211]
	v_pk_mul_f32 v[212:213], v[10:11], v[212:213]
	v_pk_mul_f32 v[206:207], v[206:207], v[12:13]
	v_pk_mul_f32 v[208:209], v[208:209], v[14:15]
	v_pk_mul_f32 v[210:211], v[210:211], v[4:5]
	v_pk_mul_f32 v[212:213], v[212:213], v[6:7]
	v_cvt_pk_bf16_f32 v4, v206, v207
	v_cvt_pk_bf16_f32 v5, v208, v209
	v_cvt_pk_bf16_f32 v6, v210, v211
	v_cvt_pk_bf16_f32 v7, v212, v213
	v_lshl_add_u64 v[8:9], v[20:21], 0, v[116:117]
	global_store_dwordx4 v[8:9], v[4:7], off
	s_cbranch_vccnz .LBB0_349
	s_andn2_b64 vcc, exec, s[0:1]
	s_cbranch_vccnz .LBB0_348
	s_barrier
	s_branch .LBB0_348
